# fused-norm epilogues of FF2-L0 and w_out: per-column scale/shift table loads issued right after the partial-sum barrier (hidden under the statistics exchange)
# baseline (speedup 1.0000x reference)
; #define PN_LOAD(k, xv) do { _Pragma("unroll") for (int mm = 0; mm < 2; ++mm) _Pragma("unroll") for (int bj = 0; bj < 2; ++bj) \
;             xv[mm][bj] = *(const u32x4*)(XH + (size_t)(u.pm * 256 + ((k) >> 1) * 128 + wr * 64 + (2 * ((k) & 1) + mm) * 16 + fr) * (2 * D) + col0 + bj * 32); } while (0)
;     __device__ __forceinline__ void epi(AccT& acc, const Unit& u, LAS unsigned char* lds, int wr, int wc, int fr, int fq) const {
;     ...
;         const int b = u.pm >> 4, col0 = u.pn * 256 + wc * 64 + 8 * fq; f32x4 gv[2][2];
; #pragma unroll
;         for (int bj = 0; bj < 2; ++bj)
; #pragma unroll
;             for (int n = 0; n < 2; ++n) gv[bj][n] = *(const f32x4*)(gt + (size_t)b * 6 * D + col0 + bj * 32 + n * 4);
;         const bf16_t* XH = (const bf16_t*)X;
;         u32x4 xa[2][2], xb[2][2];
;     ...
;         PN_LOAD(0, xa); PN_LOAD(1, xb); asm volatile("" ::: "memory"); PN_COMP(0, xa); PN_LOAD(2, xa); asm volatile("" ::: "memory"); PN_COMP(1, xb); PN_LOAD(3, xb); asm volatile("" ::: "memory"); PN_COMP(2, xa); PN_COMP(3, xb);
.LBB0_640:
	s_ashr_i32 s23, s22, 4
	s_mul_i32 s24, s23, 6
	s_ashr_i32 s25, s24, 31
	v_readlane_b32 s48, v252, 18
	s_lshl_b32 s44, s82, 8
	s_lshl_b64 s[24:25], s[24:25], 12
	v_readlane_b32 s49, v252, 19
	s_add_u32 s48, s5, s24
	s_addc_u32 s49, s3, s25
	s_lshl_b32 s23, s22, 8
	s_add_i32 s41, s23, s4
	v_readlane_b32 s62, v252, 32
	v_readlane_b32 s63, v252, 33
	v_add_u32_e32 v178, s44, v200
	v_or_b32_e32 v144, s41, v199
	s_mov_b64 s[84:85], s[62:63]
	s_mov_b64 s[86:87], s[14:15]
	v_ashrrev_i32_e32 v179, 31, v178
	v_ashrrev_i32_e32 v145, 31, v144
	v_lshlrev_b64 v[146:147], 12, v[144:145]
	v_lshl_add_u64 v[192:193], v[178:179], 1, s[84:85]
	v_lshl_add_u64 v[116:117], v[178:179], 2, s[48:49]
	v_lshl_add_u64 v[146:147], v[192:193], 0, v[146:147]
	global_load_dwordx4 v[120:123], v[116:117], off offset:16
	global_load_dwordx4 v[124:127], v[116:117], off
	global_load_dwordx4 v[112:115], v[116:117], off offset:144
	s_nop 0
	global_load_dwordx4 v[116:119], v[116:117], off offset:128
	s_nop 0
	flat_load_dwordx4 v[180:183], v[146:147]
	flat_load_dwordx4 v[168:171], v[146:147] offset:64
	v_or_b32_e32 v146, 16, v144
	v_ashrrev_i32_e32 v147, 31, v146
	v_lshlrev_b64 v[146:147], 12, v[146:147]
	v_lshl_add_u64 v[146:147], v[192:193], 0, v[146:147]
	flat_load_dwordx4 v[164:167], v[146:147]
	flat_load_dwordx4 v[160:163], v[146:147] offset:64
	v_or_b32_e32 v146, 32, v144
	v_or_b32_e32 v144, 48, v144
	v_ashrrev_i32_e32 v147, 31, v146
	v_ashrrev_i32_e32 v145, 31, v144
	v_lshlrev_b64 v[146:147], 12, v[146:147]
	v_lshlrev_b64 v[144:145], 12, v[144:145]
	v_lshl_add_u64 v[146:147], v[192:193], 0, v[146:147]
	v_lshl_add_u64 v[144:145], v[192:193], 0, v[144:145]
	flat_load_dwordx4 v[156:159], v[146:147]
	flat_load_dwordx4 v[148:151], v[146:147] offset:64
	flat_load_dwordx4 v[152:155], v[144:145]
	s_nop 0
	flat_load_dwordx4 v[144:147], v[144:145] offset:64
	v_readlane_b32 s50, v252, 20
	v_readlane_b32 s51, v252, 21
	v_readlane_b32 s52, v252, 22
	v_readlane_b32 s53, v252, 23
	v_readlane_b32 s54, v252, 24
	v_readlane_b32 s55, v252, 25
	v_readlane_b32 s56, v252, 26
	v_readlane_b32 s57, v252, 27
	v_readlane_b32 s58, v252, 28
	v_readlane_b32 s59, v252, 29
	v_readlane_b32 s60, v252, 30
	v_readlane_b32 s61, v252, 31
	s_waitcnt vmcnt(0) lgkmcnt(0)
	v_lshlrev_b32_e32 v184, 16, v180
	v_and_b32_e32 v185, 0xffff0000, v180
	v_lshlrev_b32_e32 v180, 16, v181
	v_and_b32_e32 v181, 0xffff0000, v181
	v_pk_fma_f32 v[142:143], v[142:143], v[126:127], v[180:181]
	v_pk_fma_f32 v[140:141], v[140:141], v[124:125], v[184:185]
	v_mul_f32_e32 v180, v143, v143
	v_mul_f32_e32 v179, v141, v141
	v_fmac_f32_e32 v179, v140, v140
	v_fmac_f32_e32 v180, v142, v142
	v_add_f32_e32 v179, v179, v180
	v_lshlrev_b32_e32 v180, 16, v182
	v_and_b32_e32 v181, 0xffff0000, v182
	v_lshlrev_b32_e32 v182, 16, v183
	v_and_b32_e32 v183, 0xffff0000, v183
	v_pk_fma_f32 v[138:139], v[138:139], v[122:123], v[182:183]
	v_pk_fma_f32 v[136:137], v[136:137], v[120:121], v[180:181]
	v_mul_f32_e32 v181, v139, v139
	v_mul_f32_e32 v180, v137, v137
	v_fmac_f32_e32 v180, v136, v136
	v_fmac_f32_e32 v181, v138, v138
	v_add_f32_e32 v180, v180, v181
	v_add_f32_e32 v179, v179, v180
	v_lshlrev_b32_e32 v180, 16, v168
	v_and_b32_e32 v181, 0xffff0000, v168
	v_lshlrev_b32_e32 v168, 16, v169
	v_and_b32_e32 v169, 0xffff0000, v169
	v_pk_fma_f32 v[134:135], v[134:135], v[118:119], v[168:169]
	v_pk_fma_f32 v[132:133], v[132:133], v[116:117], v[180:181]
	v_mul_f32_e32 v169, v135, v135
	v_mul_f32_e32 v168, v133, v133
	v_fmac_f32_e32 v168, v132, v132
	v_fmac_f32_e32 v169, v134, v134
	v_add_f32_e32 v168, v168, v169
	v_add_f32_e32 v179, v179, v168
	v_lshlrev_b32_e32 v180, 16, v170
	v_and_b32_e32 v181, 0xffff0000, v170
	v_lshlrev_b32_e32 v168, 16, v171
	v_and_b32_e32 v169, 0xffff0000, v171
	v_pk_fma_f32 v[168:169], v[130:131], v[114:115], v[168:169]
	v_pk_fma_f32 v[180:181], v[128:129], v[112:113], v[180:181]
	v_mul_f32_e32 v129, v169, v169
	v_mul_f32_e32 v128, v181, v181
	v_fmac_f32_e32 v128, v180, v180
	v_fmac_f32_e32 v129, v168, v168
	v_add_f32_e32 v128, v128, v129
	v_add_f32_e32 v128, v128, v179
	v_mov_b32_e32 v129, v128
	s_nop 1
	v_permlane16_swap_b32_e32 v128, v129
	v_add_f32_e32 v128, v128, v129
	v_mov_b32_e32 v129, v128
	s_nop 1
	v_permlane32_swap_b32_e32 v128, v129
	s_and_saveexec_b64 s[88:89], s[8:9]
	v_add_f32_e32 v128, v128, v129
	ds_write_b32 v222, v128
	s_or_b64 exec, exec, s[88:89]
	v_lshlrev_b32_e32 v128, 16, v164
	v_and_b32_e32 v129, 0xffff0000, v164
	v_lshlrev_b32_e32 v130, 16, v165
	v_and_b32_e32 v131, 0xffff0000, v165
	v_pk_fma_f32 v[164:165], v[110:111], v[126:127], v[130:131]
	v_pk_fma_f32 v[170:171], v[108:109], v[124:125], v[128:129]
	v_mul_f32_e32 v109, v165, v165
	v_mul_f32_e32 v108, v171, v171
	v_fmac_f32_e32 v108, v170, v170
	v_fmac_f32_e32 v109, v164, v164
	v_add_f32_e32 v128, v108, v109
	v_lshlrev_b32_e32 v108, 16, v166
	v_and_b32_e32 v109, 0xffff0000, v166
	v_lshlrev_b32_e32 v110, 16, v167
	v_and_b32_e32 v111, 0xffff0000, v167
	v_pk_fma_f32 v[184:185], v[106:107], v[122:123], v[110:111]
	v_pk_fma_f32 v[188:189], v[104:105], v[120:121], v[108:109]
	v_mul_f32_e32 v105, v185, v185
	v_mul_f32_e32 v104, v189, v189
	v_fmac_f32_e32 v104, v188, v188
	v_fmac_f32_e32 v105, v184, v184
	v_add_f32_e32 v104, v104, v105
	v_add_f32_e32 v108, v128, v104
	v_lshlrev_b32_e32 v104, 16, v160
	v_and_b32_e32 v105, 0xffff0000, v160
	v_lshlrev_b32_e32 v106, 16, v161
	v_and_b32_e32 v107, 0xffff0000, v161
	v_pk_fma_f32 v[166:167], v[102:103], v[118:119], v[106:107]
	v_pk_fma_f32 v[182:183], v[100:101], v[116:117], v[104:105]
	v_mul_f32_e32 v101, v167, v167
	v_mul_f32_e32 v100, v183, v183
	v_fmac_f32_e32 v100, v182, v182
	v_fmac_f32_e32 v101, v166, v166
; #define PN_LOAD(k, xv) do { _Pragma("unroll") for (int mm = 0; mm < 2; ++mm) _Pragma("unroll") for (int bj = 0; bj < 2; ++bj) \
;             xv[mm][bj] = *(const u32x4*)(XH + (size_t)(u.pm * 256 + ((k) >> 1) * 128 + wr * 64 + (2 * ((k) & 1) + mm) * 16 + fr) * (2 * D) + col0 + bj * 32); } while (0)
;     __device__ __forceinline__ void epi(AccT& acc, const Unit& u, LAS unsigned char* lds, int wr, int wc, int fr, int fq) const {
;     ...
;         PN_LOAD(0, xa); PN_LOAD(1, xb); asm volatile("" ::: "memory"); PN_COMP(0, xa); PN_LOAD(2, xa); asm volatile("" ::: "memory"); PN_COMP(1, xb); PN_LOAD(3, xb); asm volatile("" ::: "memory"); PN_COMP(2, xa); PN_COMP(3, xb);
	v_add_f32_e32 v100, v100, v101
	v_add_f32_e32 v104, v108, v100
	v_lshlrev_b32_e32 v100, 16, v162
	v_and_b32_e32 v101, 0xffff0000, v162
	v_lshlrev_b32_e32 v102, 16, v163
	v_and_b32_e32 v103, 0xffff0000, v163
	v_pk_fma_f32 v[186:187], v[98:99], v[114:115], v[102:103]
	v_pk_fma_f32 v[190:191], v[96:97], v[112:113], v[100:101]
	v_mul_f32_e32 v97, v187, v187
	v_mul_f32_e32 v96, v191, v191
	v_fmac_f32_e32 v96, v190, v190
	v_fmac_f32_e32 v97, v186, v186
	v_add_f32_e32 v96, v96, v97
	v_add_f32_e32 v96, v96, v104
	v_mov_b32_e32 v97, v96
	s_nop 1
	v_permlane16_swap_b32_e32 v96, v97
	v_add_f32_e32 v96, v96, v97
	v_mov_b32_e32 v97, v96
	s_nop 1
	v_permlane32_swap_b32_e32 v96, v97
	s_and_saveexec_b64 s[88:89], s[8:9]
	v_add_f32_e32 v96, v96, v97
	ds_write_b32 v222, v96 offset:256
	s_or_b64 exec, exec, s[88:89]
	v_add_u32_e32 v96, s23, v202
	v_ashrrev_i32_e32 v97, 31, v96
	v_lshlrev_b64 v[98:99], 12, v[96:97]
	v_or_b32_e32 v96, 16, v96
	v_ashrrev_i32_e32 v97, 31, v96
	v_lshlrev_b64 v[96:97], 12, v[96:97]
	v_lshl_add_u64 v[98:99], v[192:193], 0, v[98:99]
	v_lshl_add_u64 v[96:97], v[192:193], 0, v[96:97]
	flat_load_dwordx4 v[108:111], v[98:99]
	flat_load_dwordx4 v[104:107], v[98:99] offset:64
	flat_load_dwordx4 v[100:103], v[96:97]
	s_nop 0
	flat_load_dwordx4 v[96:99], v[96:97] offset:64
	v_lshlrev_b32_e32 v130, 16, v156
	v_and_b32_e32 v131, 0xffff0000, v156
	v_lshlrev_b32_e32 v128, 16, v157
	v_and_b32_e32 v129, 0xffff0000, v157
	v_pk_fma_f32 v[128:129], v[94:95], v[126:127], v[128:129]
	v_pk_fma_f32 v[130:131], v[92:93], v[124:125], v[130:131]
	v_mul_f32_e32 v93, v129, v129
	v_mul_f32_e32 v92, v131, v131
	v_fmac_f32_e32 v92, v130, v130
	v_fmac_f32_e32 v93, v128, v128
	v_add_f32_e32 v156, v92, v93
	v_lshlrev_b32_e32 v92, 16, v158
	v_and_b32_e32 v93, 0xffff0000, v158
	v_lshlrev_b32_e32 v94, 16, v159
	v_and_b32_e32 v95, 0xffff0000, v159
	v_pk_fma_f32 v[158:159], v[90:91], v[122:123], v[94:95]
	v_pk_fma_f32 v[160:161], v[88:89], v[120:121], v[92:93]
	v_mul_f32_e32 v89, v159, v159
	v_mul_f32_e32 v88, v161, v161
	v_fmac_f32_e32 v88, v160, v160
	v_fmac_f32_e32 v89, v158, v158
	v_add_f32_e32 v88, v88, v89
	v_add_f32_e32 v92, v156, v88
	v_lshlrev_b32_e32 v88, 16, v148
	v_and_b32_e32 v89, 0xffff0000, v148
	v_lshlrev_b32_e32 v90, 16, v149
	v_and_b32_e32 v91, 0xffff0000, v149
	v_pk_fma_f32 v[148:149], v[86:87], v[118:119], v[90:91]
	v_pk_fma_f32 v[156:157], v[84:85], v[116:117], v[88:89]
	v_mul_f32_e32 v85, v149, v149
	v_mul_f32_e32 v84, v157, v157
	v_fmac_f32_e32 v84, v156, v156
	v_fmac_f32_e32 v85, v148, v148
	v_add_f32_e32 v84, v84, v85
	v_add_f32_e32 v88, v92, v84
	v_lshlrev_b32_e32 v84, 16, v150
	v_and_b32_e32 v85, 0xffff0000, v150
	v_lshlrev_b32_e32 v86, 16, v151
	v_and_b32_e32 v87, 0xffff0000, v151
	v_pk_fma_f32 v[150:151], v[82:83], v[114:115], v[86:87]
	v_pk_fma_f32 v[162:163], v[80:81], v[112:113], v[84:85]
	v_mul_f32_e32 v81, v151, v151
	v_mul_f32_e32 v80, v163, v163
	v_fmac_f32_e32 v80, v162, v162
	v_fmac_f32_e32 v81, v150, v150
	v_add_f32_e32 v80, v80, v81
	v_add_f32_e32 v80, v80, v88
	v_mov_b32_e32 v81, v80
	s_nop 1
	v_permlane16_swap_b32_e32 v80, v81
	v_add_f32_e32 v80, v80, v81
	v_mov_b32_e32 v81, v80
	s_nop 1
	v_permlane32_swap_b32_e32 v80, v81
	s_and_saveexec_b64 s[88:89], s[8:9]
	v_add_f32_e32 v80, v80, v81
	ds_write_b32 v222, v80 offset:512
	s_or_b64 exec, exec, s[88:89]
	v_lshlrev_b32_e32 v82, 16, v152
	v_and_b32_e32 v83, 0xffff0000, v152
	v_lshlrev_b32_e32 v80, 16, v153
	v_and_b32_e32 v81, 0xffff0000, v153
	v_pk_fma_f32 v[80:81], v[78:79], v[126:127], v[80:81]
	v_pk_fma_f32 v[84:85], v[76:77], v[124:125], v[82:83]
	v_mul_f32_e32 v77, v81, v81
	v_mul_f32_e32 v76, v85, v85
	v_fmac_f32_e32 v76, v84, v84
	v_fmac_f32_e32 v77, v80, v80
	v_add_f32_e32 v82, v76, v77
	v_lshlrev_b32_e32 v76, 16, v154
	v_and_b32_e32 v77, 0xffff0000, v154
	v_lshlrev_b32_e32 v78, 16, v155
	v_and_b32_e32 v79, 0xffff0000, v155
	v_pk_fma_f32 v[88:89], v[74:75], v[122:123], v[78:79]
	v_pk_fma_f32 v[92:93], v[72:73], v[120:121], v[76:77]
	v_mul_f32_e32 v73, v89, v89
	v_mul_f32_e32 v72, v93, v93
	v_fmac_f32_e32 v72, v92, v92
	v_fmac_f32_e32 v73, v88, v88
	v_add_f32_e32 v72, v72, v73
	v_add_f32_e32 v76, v82, v72
	v_lshlrev_b32_e32 v72, 16, v144
	v_and_b32_e32 v73, 0xffff0000, v144
	v_lshlrev_b32_e32 v74, 16, v145
	v_and_b32_e32 v75, 0xffff0000, v145
	v_pk_fma_f32 v[82:83], v[70:71], v[118:119], v[74:75]
	v_pk_fma_f32 v[86:87], v[68:69], v[116:117], v[72:73]
	v_mul_f32_e32 v69, v83, v83
	v_mul_f32_e32 v68, v87, v87
	v_fmac_f32_e32 v68, v86, v86
	v_fmac_f32_e32 v69, v82, v82
	v_add_f32_e32 v68, v68, v69
	v_add_f32_e32 v72, v76, v68
	v_lshlrev_b32_e32 v68, 16, v146
	v_and_b32_e32 v69, 0xffff0000, v146
	v_lshlrev_b32_e32 v70, 16, v147
	v_and_b32_e32 v71, 0xffff0000, v147
	v_pk_fma_f32 v[90:91], v[66:67], v[114:115], v[70:71]
	v_pk_fma_f32 v[94:95], v[64:65], v[112:113], v[68:69]
	v_mul_f32_e32 v65, v91, v91
	v_mul_f32_e32 v64, v95, v95
	v_fmac_f32_e32 v64, v94, v94
	v_fmac_f32_e32 v65, v90, v90
	v_add_f32_e32 v64, v64, v65
	v_add_f32_e32 v64, v64, v72
	v_mov_b32_e32 v65, v64
	s_nop 1
	v_permlane16_swap_b32_e32 v64, v65
	v_add_f32_e32 v64, v64, v65
	v_mov_b32_e32 v65, v64
	s_nop 1
	v_permlane32_swap_b32_e32 v64, v65
	s_and_saveexec_b64 s[88:89], s[8:9]
	v_add_f32_e32 v64, v64, v65
	ds_write_b32 v222, v64 offset:768
	s_or_b64 exec, exec, s[88:89]
	v_add_u32_e32 v64, s41, v212
	v_ashrrev_i32_e32 v65, 31, v64
	v_lshlrev_b64 v[66:67], 12, v[64:65]
	v_or_b32_e32 v64, 16, v64
	v_ashrrev_i32_e32 v65, 31, v64
	v_lshlrev_b64 v[64:65], 12, v[64:65]
	v_lshl_add_u64 v[66:67], v[192:193], 0, v[66:67]
	v_lshl_add_u64 v[64:65], v[192:193], 0, v[64:65]
	flat_load_dwordx4 v[76:79], v[66:67]
	flat_load_dwordx4 v[72:75], v[66:67] offset:64
	flat_load_dwordx4 v[68:71], v[64:65]
	s_nop 0
	flat_load_dwordx4 v[64:67], v[64:65] offset:64
	s_waitcnt vmcnt(0) lgkmcnt(0)
; #define PN_LOAD(k, xv) do { _Pragma("unroll") for (int mm = 0; mm < 2; ++mm) _Pragma("unroll") for (int bj = 0; bj < 2; ++bj) \
;             xv[mm][bj] = *(const u32x4*)(XH + (size_t)(u.pm * 256 + ((k) >> 1) * 128 + wr * 64 + (2 * ((k) & 1) + mm) * 16 + fr) * (2 * D) + col0 + bj * 32); } while (0)
;     __device__ __forceinline__ void epi(AccT& acc, const Unit& u, LAS unsigned char* lds, int wr, int wc, int fr, int fq) const {
;     ...
;         PN_LOAD(0, xa); PN_LOAD(1, xb); asm volatile("" ::: "memory"); PN_COMP(0, xa); PN_LOAD(2, xa); asm volatile("" ::: "memory"); PN_COMP(1, xb); PN_LOAD(3, xb); asm volatile("" ::: "memory"); PN_COMP(2, xa); PN_COMP(3, xb);
	v_lshlrev_b32_e32 v144, 16, v108
	v_and_b32_e32 v145, 0xffff0000, v108
	v_lshlrev_b32_e32 v108, 16, v109
	v_and_b32_e32 v109, 0xffff0000, v109
	v_pk_fma_f32 v[62:63], v[62:63], v[126:127], v[108:109]
	v_pk_fma_f32 v[60:61], v[60:61], v[124:125], v[144:145]
	v_mul_f32_e32 v109, v63, v63
	v_mul_f32_e32 v108, v61, v61
	v_fmac_f32_e32 v108, v60, v60
	v_fmac_f32_e32 v109, v62, v62
	v_add_f32_e32 v144, v108, v109
	v_lshlrev_b32_e32 v108, 16, v110
	v_and_b32_e32 v109, 0xffff0000, v110
	v_lshlrev_b32_e32 v110, 16, v111
	v_and_b32_e32 v111, 0xffff0000, v111
	v_pk_fma_f32 v[58:59], v[58:59], v[122:123], v[110:111]
	v_pk_fma_f32 v[56:57], v[56:57], v[120:121], v[108:109]
	v_mul_f32_e32 v109, v59, v59
	v_mul_f32_e32 v108, v57, v57
	v_fmac_f32_e32 v108, v56, v56
	v_fmac_f32_e32 v109, v58, v58
	v_add_f32_e32 v108, v108, v109
	v_add_f32_e32 v110, v144, v108
	v_lshlrev_b32_e32 v108, 16, v104
	v_and_b32_e32 v109, 0xffff0000, v104
	v_lshlrev_b32_e32 v104, 16, v105
	v_and_b32_e32 v105, 0xffff0000, v105
	v_pk_fma_f32 v[54:55], v[54:55], v[118:119], v[104:105]
	v_pk_fma_f32 v[52:53], v[52:53], v[116:117], v[108:109]
	v_mul_f32_e32 v105, v55, v55
	v_mul_f32_e32 v104, v53, v53
	v_fmac_f32_e32 v104, v52, v52
	v_fmac_f32_e32 v105, v54, v54
	v_add_f32_e32 v104, v104, v105
	v_add_f32_e32 v108, v110, v104
	v_lshlrev_b32_e32 v104, 16, v106
	v_and_b32_e32 v105, 0xffff0000, v106
	v_lshlrev_b32_e32 v106, 16, v107
	v_and_b32_e32 v107, 0xffff0000, v107
	v_pk_fma_f32 v[50:51], v[50:51], v[114:115], v[106:107]
	v_pk_fma_f32 v[48:49], v[48:49], v[112:113], v[104:105]
	v_mul_f32_e32 v105, v51, v51
	v_mul_f32_e32 v104, v49, v49
	v_fmac_f32_e32 v104, v48, v48
	v_fmac_f32_e32 v105, v50, v50
	v_add_f32_e32 v104, v104, v105
	v_add_f32_e32 v104, v104, v108
	v_mov_b32_e32 v105, v104
	s_nop 1
	v_permlane16_swap_b32_e32 v104, v105
	v_add_f32_e32 v104, v104, v105
	v_mov_b32_e32 v105, v104
	s_nop 1
	v_permlane32_swap_b32_e32 v104, v105
	s_and_saveexec_b64 s[88:89], s[8:9]
	v_add_f32_e32 v104, v104, v105
	ds_write_b32 v223, v104
	s_or_b64 exec, exec, s[88:89]
	v_lshlrev_b32_e32 v104, 16, v100
	v_and_b32_e32 v105, 0xffff0000, v100
	v_lshlrev_b32_e32 v100, 16, v101
	v_and_b32_e32 v101, 0xffff0000, v101
	v_pk_fma_f32 v[46:47], v[46:47], v[126:127], v[100:101]
	v_pk_fma_f32 v[44:45], v[44:45], v[124:125], v[104:105]
	v_mul_f32_e32 v101, v47, v47
	v_mul_f32_e32 v100, v45, v45
	v_fmac_f32_e32 v100, v44, v44
	v_fmac_f32_e32 v101, v46, v46
	v_add_f32_e32 v104, v100, v101
	v_lshlrev_b32_e32 v100, 16, v102
	v_and_b32_e32 v101, 0xffff0000, v102
	v_lshlrev_b32_e32 v102, 16, v103
	v_and_b32_e32 v103, 0xffff0000, v103
	v_pk_fma_f32 v[42:43], v[42:43], v[122:123], v[102:103]
	v_pk_fma_f32 v[40:41], v[40:41], v[120:121], v[100:101]
	v_mul_f32_e32 v101, v43, v43
	v_mul_f32_e32 v100, v41, v41
	v_fmac_f32_e32 v100, v40, v40
	v_fmac_f32_e32 v101, v42, v42
	v_add_f32_e32 v100, v100, v101
	v_add_f32_e32 v102, v104, v100
	v_lshlrev_b32_e32 v100, 16, v96
	v_and_b32_e32 v101, 0xffff0000, v96
	v_lshlrev_b32_e32 v96, 16, v97
	v_and_b32_e32 v97, 0xffff0000, v97
	v_pk_fma_f32 v[38:39], v[38:39], v[118:119], v[96:97]
	v_pk_fma_f32 v[36:37], v[36:37], v[116:117], v[100:101]
	v_mul_f32_e32 v97, v39, v39
	v_mul_f32_e32 v96, v37, v37
	v_fmac_f32_e32 v96, v36, v36
	v_fmac_f32_e32 v97, v38, v38
	v_add_f32_e32 v96, v96, v97
	v_add_f32_e32 v100, v102, v96
	v_lshlrev_b32_e32 v96, 16, v98
	v_and_b32_e32 v97, 0xffff0000, v98
	v_lshlrev_b32_e32 v98, 16, v99
	v_and_b32_e32 v99, 0xffff0000, v99
	v_pk_fma_f32 v[34:35], v[34:35], v[114:115], v[98:99]
	v_pk_fma_f32 v[32:33], v[32:33], v[112:113], v[96:97]
	v_mul_f32_e32 v97, v35, v35
	v_mul_f32_e32 v96, v33, v33
	v_fmac_f32_e32 v96, v32, v32
	v_fmac_f32_e32 v97, v34, v34
	v_add_f32_e32 v96, v96, v97
	v_add_f32_e32 v96, v96, v100
	v_mov_b32_e32 v97, v96
	s_nop 1
	v_permlane16_swap_b32_e32 v96, v97
	v_add_f32_e32 v96, v96, v97
	v_mov_b32_e32 v97, v96
	s_nop 1
	v_permlane32_swap_b32_e32 v96, v97
	s_and_saveexec_b64 s[88:89], s[8:9]
	v_add_f32_e32 v96, v96, v97
	ds_write_b32 v223, v96 offset:256
	s_or_b64 exec, exec, s[88:89]
	v_lshlrev_b32_e32 v96, 16, v76
	v_and_b32_e32 v97, 0xffff0000, v76
	v_lshlrev_b32_e32 v76, 16, v77
	v_and_b32_e32 v77, 0xffff0000, v77
	v_pk_fma_f32 v[30:31], v[30:31], v[126:127], v[76:77]
	v_pk_fma_f32 v[28:29], v[28:29], v[124:125], v[96:97]
	v_mul_f32_e32 v77, v31, v31
	v_mul_f32_e32 v76, v29, v29
	v_fmac_f32_e32 v76, v28, v28
	v_fmac_f32_e32 v77, v30, v30
	v_add_f32_e32 v96, v76, v77
	v_lshlrev_b32_e32 v76, 16, v78
	v_and_b32_e32 v77, 0xffff0000, v78
	v_lshlrev_b32_e32 v78, 16, v79
	v_and_b32_e32 v79, 0xffff0000, v79
; #define LAS __attribute__((address_space(3)))
; #define ESTAMP(i) do { if (PROBE_K >= 100 && MODE == 1 && blockIdx.x == 0 && wr * 4 + wc == 0 && fr + 16 * fq == 0 && tmo != nullptr) { ((unsigned long long*)tmo)[25600 + 64 + (i)] = __builtin_amdgcn_s_memrealtime(); } } while (0)
; #define PN_LOAD(k, xv) do { _Pragma("unroll") for (int mm = 0; mm < 2; ++mm) _Pragma("unroll") for (int bj = 0; bj < 2; ++bj) \
;             xv[mm][bj] = *(const u32x4*)(XH + (size_t)(u.pm * 256 + ((k) >> 1) * 128 + wr * 64 + (2 * ((k) & 1) + mm) * 16 + fr) * (2 * D) + col0 + bj * 32); } while (0)
;     __device__ __forceinline__ void epi(AccT& acc, const Unit& u, LAS unsigned char* lds, int wr, int wc, int fr, int fq) const {
;     ...
;         PN_LOAD(0, xa); PN_LOAD(1, xb); asm volatile("" ::: "memory"); PN_COMP(0, xa); PN_LOAD(2, xa); asm volatile("" ::: "memory"); PN_COMP(1, xb); PN_LOAD(3, xb); asm volatile("" ::: "memory"); PN_COMP(2, xa); PN_COMP(3, xb);
;     ...
;         asm volatile("s_waitcnt lgkmcnt(0)" ::: "memory"); __builtin_amdgcn_s_barrier(); asm volatile("" ::: "memory");
;         ESTAMP(1);
;         const int row = wid * 32 + (lane & 31);
;         if (lane < 32) { const f32x4 p4 = *(const LAS f32x4*)(Pl + row * 4); const float tot = (p4[0] + p4[1]) + (p4[2] + p4[3]);
;             __hip_atomic_store(xbuf + (size_t)(u.pm * 256 + row) * 4 + u.pn, __builtin_bit_cast(unsigned, tot), __ATOMIC_RELAXED, __HIP_MEMORY_SCOPE_AGENT); }
;     ...
;             if (tid < 256) { const int c = u.pn * 256 + tid; svl[tid] = wf[c] * (1.f + shp[(size_t)b * 6 * D + D + c]); tvl[tid] = shp[(size_t)b * 6 * D + c]; }
	v_pk_fma_f32 v[26:27], v[26:27], v[122:123], v[78:79]
	v_pk_fma_f32 v[24:25], v[24:25], v[120:121], v[76:77]
	v_mul_f32_e32 v77, v27, v27
	v_mul_f32_e32 v76, v25, v25
	v_fmac_f32_e32 v76, v24, v24
	v_fmac_f32_e32 v77, v26, v26
	v_add_f32_e32 v76, v76, v77
	v_add_f32_e32 v78, v96, v76
	v_lshlrev_b32_e32 v76, 16, v72
	v_and_b32_e32 v77, 0xffff0000, v72
	v_lshlrev_b32_e32 v72, 16, v73
	v_and_b32_e32 v73, 0xffff0000, v73
	v_pk_fma_f32 v[22:23], v[22:23], v[118:119], v[72:73]
	v_pk_fma_f32 v[20:21], v[20:21], v[116:117], v[76:77]
	v_mul_f32_e32 v73, v23, v23
	v_mul_f32_e32 v72, v21, v21
	v_fmac_f32_e32 v72, v20, v20
	v_fmac_f32_e32 v73, v22, v22
	v_add_f32_e32 v72, v72, v73
	v_add_f32_e32 v76, v78, v72
	v_lshlrev_b32_e32 v72, 16, v74
	v_and_b32_e32 v73, 0xffff0000, v74
	v_lshlrev_b32_e32 v74, 16, v75
	v_and_b32_e32 v75, 0xffff0000, v75
	v_pk_fma_f32 v[18:19], v[18:19], v[114:115], v[74:75]
	v_pk_fma_f32 v[16:17], v[16:17], v[112:113], v[72:73]
	v_mul_f32_e32 v73, v19, v19
	v_mul_f32_e32 v72, v17, v17
	v_fmac_f32_e32 v72, v16, v16
	v_fmac_f32_e32 v73, v18, v18
	v_add_f32_e32 v72, v72, v73
	v_add_f32_e32 v72, v72, v76
	v_mov_b32_e32 v73, v72
	s_nop 1
	v_permlane16_swap_b32_e32 v72, v73
	v_add_f32_e32 v72, v72, v73
	v_mov_b32_e32 v73, v72
	s_nop 1
	v_permlane32_swap_b32_e32 v72, v73
	s_and_saveexec_b64 s[88:89], s[8:9]
	v_add_f32_e32 v72, v72, v73
	ds_write_b32 v223, v72 offset:512
	s_or_b64 exec, exec, s[88:89]
	v_lshlrev_b32_e32 v72, 16, v68
	v_and_b32_e32 v73, 0xffff0000, v68
	v_lshlrev_b32_e32 v68, 16, v69
	v_and_b32_e32 v69, 0xffff0000, v69
	v_pk_fma_f32 v[14:15], v[14:15], v[126:127], v[68:69]
	v_pk_fma_f32 v[12:13], v[12:13], v[124:125], v[72:73]
	v_mul_f32_e32 v69, v15, v15
	v_mul_f32_e32 v68, v13, v13
	v_fmac_f32_e32 v68, v12, v12
	v_fmac_f32_e32 v69, v14, v14
	v_add_f32_e32 v72, v68, v69
	v_lshlrev_b32_e32 v68, 16, v70
	v_and_b32_e32 v69, 0xffff0000, v70
	v_lshlrev_b32_e32 v70, 16, v71
	v_and_b32_e32 v71, 0xffff0000, v71
	v_pk_fma_f32 v[10:11], v[10:11], v[122:123], v[70:71]
	v_pk_fma_f32 v[8:9], v[8:9], v[120:121], v[68:69]
	v_mul_f32_e32 v69, v11, v11
	v_mul_f32_e32 v68, v9, v9
	v_fmac_f32_e32 v68, v8, v8
	v_fmac_f32_e32 v69, v10, v10
	v_add_f32_e32 v68, v68, v69
	v_add_f32_e32 v70, v72, v68
	v_lshlrev_b32_e32 v68, 16, v64
	v_and_b32_e32 v69, 0xffff0000, v64
	v_lshlrev_b32_e32 v64, 16, v65
	v_and_b32_e32 v65, 0xffff0000, v65
	v_pk_fma_f32 v[6:7], v[6:7], v[118:119], v[64:65]
	v_pk_fma_f32 v[4:5], v[4:5], v[116:117], v[68:69]
	v_mul_f32_e32 v65, v7, v7
	v_mul_f32_e32 v64, v5, v5
	v_fmac_f32_e32 v64, v4, v4
	v_fmac_f32_e32 v65, v6, v6
	v_add_f32_e32 v64, v64, v65
	v_add_f32_e32 v68, v70, v64
	v_lshlrev_b32_e32 v64, 16, v66
	v_and_b32_e32 v65, 0xffff0000, v66
	v_lshlrev_b32_e32 v66, 16, v67
	v_and_b32_e32 v67, 0xffff0000, v67
	v_pk_fma_f32 v[2:3], v[2:3], v[114:115], v[66:67]
	v_pk_fma_f32 v[0:1], v[0:1], v[112:113], v[64:65]
	v_mul_f32_e32 v65, v3, v3
	v_mul_f32_e32 v64, v1, v1
	v_fmac_f32_e32 v64, v0, v0
	v_fmac_f32_e32 v65, v2, v2
	v_add_f32_e32 v64, v64, v65
	v_add_f32_e32 v64, v64, v68
	v_mov_b32_e32 v65, v64
	s_nop 1
	v_permlane16_swap_b32_e32 v64, v65
	v_add_f32_e32 v64, v64, v65
	v_mov_b32_e32 v65, v64
	s_nop 1
	v_permlane32_swap_b32_e32 v64, v65
	s_and_saveexec_b64 s[88:89], s[8:9]
	v_add_f32_e32 v64, v64, v65
	ds_write_b32 v223, v64 offset:768
	s_or_b64 exec, exec, s[88:89]
	s_waitcnt lgkmcnt(0)
	s_barrier
	s_and_saveexec_b64 s[88:89], s[16:17]
	v_add_u32_e32 v64, s44, v201
	v_readlane_b32 s44, v252, 54
	v_ashrrev_i32_e32 v65, 31, v64
	v_readlane_b32 s48, v252, 52
	s_add_u32 s24, s44, s24
	v_readlane_b32 s44, v252, 55
	v_lshlrev_b64 v[64:65], 2, v[64:65]
	v_readlane_b32 s49, v252, 53
	s_addc_u32 s25, s44, s25
	s_nop 0
	v_lshl_add_u64 v[68:69], s[48:49], 0, v[64:65]
	v_lshl_add_u64 v[64:65], s[24:25], 0, v[64:65]
	global_load_dword v228, v[68:69], off
	v_add_co_u32_e32 v68, vcc, 0x1000, v64
	global_load_dword v229, v[64:65], off
	s_nop 0
	v_addc_co_u32_e32 v69, vcc, 0, v65, vcc
	global_load_dword v230, v[68:69], off
	s_mov_b64 exec, s[88:89]
	v_add_u32_e32 v64, s23, v203
	v_ashrrev_i32_e32 v65, 31, v64
	s_and_saveexec_b64 s[88:89], s[10:11]
	s_cbranch_execz .LBB0_658
	ds_read_b128 v[66:69], v218
	s_ashr_i32 s83, s82, 31
	s_waitcnt lgkmcnt(0)
	v_mov_b32_e32 v70, v67
	v_mov_b32_e32 v71, v68
	v_mov_b32_e32 v67, v69
	v_pk_add_f32 v[66:67], v[70:71], v[66:67]
	v_lshl_add_u64 v[68:69], v[64:65], 4, s[64:65]
	v_pk_add_f32 v[66:67], v[66:67], v[66:67] op_sel:[0,1] op_sel_hi:[1,0]
	v_lshl_add_u64 v[68:69], s[82:83], 2, v[68:69]
	global_store_dword v[68:69], v66, off sc1

;     __device__ __forceinline__ void epi(AccT& acc, const Unit& u, LAS unsigned char* lds, int wr, int wc, int fr, int fq) const {
;     ...
;             if (tid < 256) { const int c = u.pn * 256 + tid; svl[tid] = wf[c] * (1.f + shp[(size_t)b * 6 * D + D + c]); tvl[tid] = shp[(size_t)b * 6 * D + c]; }
;             asm volatile("s_waitcnt vmcnt(0) lgkmcnt(0)" ::: "memory"); __builtin_amdgcn_s_barrier(); asm volatile("" ::: "memory");
.LBB0_681:
	s_or_b64 exec, exec, s[82:83]
	s_waitcnt lgkmcnt(0)
	s_barrier
	s_and_saveexec_b64 s[22:23], s[16:17]
	s_cbranch_execz .LBB0_683
	s_waitcnt vmcnt(0)
	ds_write_b32 v206, v229
	v_add_f32_e32 v230, 1.0, v230
	v_mul_f32_e32 v228, v228, v230
	ds_write_b32 v205, v228

; #define PN_LOAD(k, xv) do { _Pragma("unroll") for (int mm = 0; mm < 2; ++mm) _Pragma("unroll") for (int bj = 0; bj < 2; ++bj) \
;             xv[mm][bj] = *(const u32x4*)(XH + (size_t)(u.pm * 256 + ((k) >> 1) * 128 + wr * 64 + (2 * ((k) & 1) + mm) * 16 + fr) * (2 * D) + col0 + bj * 32); } while (0)
;     __device__ __forceinline__ void epi(AccT& acc, const Unit& u, LAS unsigned char* lds, int wr, int wc, int fr, int fq) const {
;     ...
;         const int b = u.pm >> 4, col0 = u.pn * 256 + wc * 64 + 8 * fq; f32x4 gv[2][2];
; #pragma unroll
;         for (int bj = 0; bj < 2; ++bj)
; #pragma unroll
;             for (int n = 0; n < 2; ++n) gv[bj][n] = *(const f32x4*)(gt + (size_t)b * 6 * D + col0 + bj * 32 + n * 4);
;         const bf16_t* XH = (const bf16_t*)X;
;         u32x4 xa[2][2], xb[2][2];
;     ...
;         PN_LOAD(0, xa); PN_LOAD(1, xb); asm volatile("" ::: "memory"); PN_COMP(0, xa); PN_LOAD(2, xa); asm volatile("" ::: "memory"); PN_COMP(1, xb); PN_LOAD(3, xb); asm volatile("" ::: "memory"); PN_COMP(2, xa); PN_COMP(3, xb);
.LBB0_1001:
	s_ashr_i32 s24, s80, 4
	s_mul_i32 s24, s24, 6
	s_ashr_i32 s25, s24, 31
	s_lshl_b32 s63, s74, 8
	s_lshl_b64 s[26:27], s[24:25], 12
	s_add_u32 s24, s81, s26
	v_readlane_b32 s25, v252, 57
	s_addc_u32 s25, s25, s27
	s_lshl_b32 s75, s80, 8
	v_readlane_b32 s44, v252, 18
	s_add_i32 s36, s75, s6
	v_readlane_b32 s58, v252, 32
	v_readlane_b32 s59, v252, 33
	v_add_u32_e32 v178, s63, v200
	v_or_b32_e32 v144, s36, v199
	s_mov_b64 s[76:77], s[58:59]
	s_mov_b64 s[78:79], s[16:17]
	v_ashrrev_i32_e32 v179, 31, v178
	v_ashrrev_i32_e32 v145, 31, v144
	v_lshlrev_b64 v[146:147], 12, v[144:145]
	v_lshl_add_u64 v[192:193], v[178:179], 1, s[76:77]
	v_lshl_add_u64 v[116:117], v[178:179], 2, s[24:25]
	v_lshl_add_u64 v[146:147], v[192:193], 0, v[146:147]
	global_load_dwordx4 v[120:123], v[116:117], off offset:16
	global_load_dwordx4 v[124:127], v[116:117], off
	global_load_dwordx4 v[112:115], v[116:117], off offset:144
	s_nop 0
	global_load_dwordx4 v[116:119], v[116:117], off offset:128
	s_nop 0
	flat_load_dwordx4 v[180:183], v[146:147]
	flat_load_dwordx4 v[168:171], v[146:147] offset:64
	v_or_b32_e32 v146, 16, v144
	v_ashrrev_i32_e32 v147, 31, v146
	v_lshlrev_b64 v[146:147], 12, v[146:147]
	v_lshl_add_u64 v[146:147], v[192:193], 0, v[146:147]
	flat_load_dwordx4 v[164:167], v[146:147]
	flat_load_dwordx4 v[160:163], v[146:147] offset:64
	v_or_b32_e32 v146, 32, v144
	v_or_b32_e32 v144, 48, v144
	v_ashrrev_i32_e32 v147, 31, v146
	v_ashrrev_i32_e32 v145, 31, v144
	v_lshlrev_b64 v[146:147], 12, v[146:147]
	v_lshlrev_b64 v[144:145], 12, v[144:145]
	v_lshl_add_u64 v[146:147], v[192:193], 0, v[146:147]
	v_lshl_add_u64 v[144:145], v[192:193], 0, v[144:145]
	flat_load_dwordx4 v[156:159], v[146:147]
	flat_load_dwordx4 v[148:151], v[146:147] offset:64
	flat_load_dwordx4 v[152:155], v[144:145]
	s_nop 0
	flat_load_dwordx4 v[144:147], v[144:145] offset:64
	v_readlane_b32 s45, v252, 19
	v_readlane_b32 s46, v252, 20
	v_readlane_b32 s47, v252, 21
	v_readlane_b32 s48, v252, 22
	v_readlane_b32 s49, v252, 23
	v_readlane_b32 s50, v252, 24
	v_readlane_b32 s51, v252, 25
	v_readlane_b32 s52, v252, 26
	v_readlane_b32 s53, v252, 27
	v_readlane_b32 s54, v252, 28
	v_readlane_b32 s55, v252, 29
	v_readlane_b32 s56, v252, 30
	v_readlane_b32 s57, v252, 31
	s_waitcnt vmcnt(0) lgkmcnt(0)
	v_lshlrev_b32_e32 v184, 16, v180
	v_and_b32_e32 v185, 0xffff0000, v180
	v_lshlrev_b32_e32 v180, 16, v181
	v_and_b32_e32 v181, 0xffff0000, v181
	v_pk_fma_f32 v[142:143], v[142:143], v[126:127], v[180:181]
	v_pk_fma_f32 v[140:141], v[140:141], v[124:125], v[184:185]
	v_mul_f32_e32 v180, v143, v143
	v_mul_f32_e32 v179, v141, v141
	v_fmac_f32_e32 v179, v140, v140
	v_fmac_f32_e32 v180, v142, v142
	v_add_f32_e32 v179, v179, v180
	v_lshlrev_b32_e32 v180, 16, v182
	v_and_b32_e32 v181, 0xffff0000, v182
	v_lshlrev_b32_e32 v182, 16, v183
	v_and_b32_e32 v183, 0xffff0000, v183
	v_pk_fma_f32 v[138:139], v[138:139], v[122:123], v[182:183]
	v_pk_fma_f32 v[136:137], v[136:137], v[120:121], v[180:181]
	v_mul_f32_e32 v181, v139, v139
	v_mul_f32_e32 v180, v137, v137
	v_fmac_f32_e32 v180, v136, v136
	v_fmac_f32_e32 v181, v138, v138
	v_add_f32_e32 v180, v180, v181
	v_add_f32_e32 v179, v179, v180
	v_lshlrev_b32_e32 v180, 16, v168
	v_and_b32_e32 v181, 0xffff0000, v168
	v_lshlrev_b32_e32 v168, 16, v169
	v_and_b32_e32 v169, 0xffff0000, v169
	v_pk_fma_f32 v[134:135], v[134:135], v[118:119], v[168:169]
	v_pk_fma_f32 v[132:133], v[132:133], v[116:117], v[180:181]
	v_mul_f32_e32 v169, v135, v135
	v_mul_f32_e32 v168, v133, v133
	v_fmac_f32_e32 v168, v132, v132
	v_fmac_f32_e32 v169, v134, v134
	v_add_f32_e32 v168, v168, v169
	v_add_f32_e32 v179, v179, v168
	v_lshlrev_b32_e32 v180, 16, v170
	v_and_b32_e32 v181, 0xffff0000, v170
	v_lshlrev_b32_e32 v168, 16, v171
	v_and_b32_e32 v169, 0xffff0000, v171
	v_pk_fma_f32 v[168:169], v[130:131], v[114:115], v[168:169]
	v_pk_fma_f32 v[180:181], v[128:129], v[112:113], v[180:181]
	v_mul_f32_e32 v129, v169, v169
	v_mul_f32_e32 v128, v181, v181
	v_fmac_f32_e32 v128, v180, v180
	v_fmac_f32_e32 v129, v168, v168
	v_add_f32_e32 v128, v128, v129
	v_add_f32_e32 v128, v128, v179
	v_mov_b32_e32 v129, v128
	s_nop 1
	v_permlane16_swap_b32_e32 v128, v129
	v_add_f32_e32 v128, v128, v129
	v_mov_b32_e32 v129, v128
	s_nop 1
	v_permlane32_swap_b32_e32 v128, v129
	s_and_saveexec_b64 s[24:25], s[10:11]
	v_add_f32_e32 v128, v128, v129
	ds_write_b32 v222, v128
	s_or_b64 exec, exec, s[24:25]
	v_lshlrev_b32_e32 v128, 16, v164
	v_and_b32_e32 v129, 0xffff0000, v164
	v_lshlrev_b32_e32 v130, 16, v165
	v_and_b32_e32 v131, 0xffff0000, v165
	v_pk_fma_f32 v[164:165], v[110:111], v[126:127], v[130:131]
	v_pk_fma_f32 v[170:171], v[108:109], v[124:125], v[128:129]
	v_mul_f32_e32 v109, v165, v165
	v_mul_f32_e32 v108, v171, v171
	v_fmac_f32_e32 v108, v170, v170
	v_fmac_f32_e32 v109, v164, v164
	v_add_f32_e32 v128, v108, v109
	v_lshlrev_b32_e32 v108, 16, v166
	v_and_b32_e32 v109, 0xffff0000, v166
	v_lshlrev_b32_e32 v110, 16, v167
	v_and_b32_e32 v111, 0xffff0000, v167
	v_pk_fma_f32 v[184:185], v[106:107], v[122:123], v[110:111]
	v_pk_fma_f32 v[188:189], v[104:105], v[120:121], v[108:109]
	v_mul_f32_e32 v105, v185, v185
	v_mul_f32_e32 v104, v189, v189
	v_fmac_f32_e32 v104, v188, v188
	v_fmac_f32_e32 v105, v184, v184
	v_add_f32_e32 v104, v104, v105
	v_add_f32_e32 v108, v128, v104
	v_lshlrev_b32_e32 v104, 16, v160
	v_and_b32_e32 v105, 0xffff0000, v160
	v_lshlrev_b32_e32 v106, 16, v161
	v_and_b32_e32 v107, 0xffff0000, v161
	v_pk_fma_f32 v[166:167], v[102:103], v[118:119], v[106:107]
	v_pk_fma_f32 v[182:183], v[100:101], v[116:117], v[104:105]
	v_mul_f32_e32 v101, v167, v167
	v_mul_f32_e32 v100, v183, v183
	v_fmac_f32_e32 v100, v182, v182
; #define PN_LOAD(k, xv) do { _Pragma("unroll") for (int mm = 0; mm < 2; ++mm) _Pragma("unroll") for (int bj = 0; bj < 2; ++bj) \
;             xv[mm][bj] = *(const u32x4*)(XH + (size_t)(u.pm * 256 + ((k) >> 1) * 128 + wr * 64 + (2 * ((k) & 1) + mm) * 16 + fr) * (2 * D) + col0 + bj * 32); } while (0)
;     __device__ __forceinline__ void epi(AccT& acc, const Unit& u, LAS unsigned char* lds, int wr, int wc, int fr, int fq) const {
;     ...
;         PN_LOAD(0, xa); PN_LOAD(1, xb); asm volatile("" ::: "memory"); PN_COMP(0, xa); PN_LOAD(2, xa); asm volatile("" ::: "memory"); PN_COMP(1, xb); PN_LOAD(3, xb); asm volatile("" ::: "memory"); PN_COMP(2, xa); PN_COMP(3, xb);
	v_fmac_f32_e32 v101, v166, v166
	v_add_f32_e32 v100, v100, v101
	v_add_f32_e32 v104, v108, v100
	v_lshlrev_b32_e32 v100, 16, v162
	v_and_b32_e32 v101, 0xffff0000, v162
	v_lshlrev_b32_e32 v102, 16, v163
	v_and_b32_e32 v103, 0xffff0000, v163
	v_pk_fma_f32 v[186:187], v[98:99], v[114:115], v[102:103]
	v_pk_fma_f32 v[190:191], v[96:97], v[112:113], v[100:101]
	v_mul_f32_e32 v97, v187, v187
	v_mul_f32_e32 v96, v191, v191
	v_fmac_f32_e32 v96, v190, v190
	v_fmac_f32_e32 v97, v186, v186
	v_add_f32_e32 v96, v96, v97
	v_add_f32_e32 v96, v96, v104
	v_mov_b32_e32 v97, v96
	s_nop 1
	v_permlane16_swap_b32_e32 v96, v97
	v_add_f32_e32 v96, v96, v97
	v_mov_b32_e32 v97, v96
	s_nop 1
	v_permlane32_swap_b32_e32 v96, v97
	s_and_saveexec_b64 s[24:25], s[10:11]
	v_add_f32_e32 v96, v96, v97
	ds_write_b32 v222, v96 offset:256
	s_or_b64 exec, exec, s[24:25]
	v_add_u32_e32 v96, s75, v202
	v_ashrrev_i32_e32 v97, 31, v96
	v_lshlrev_b64 v[98:99], 12, v[96:97]
	v_or_b32_e32 v96, 16, v96
	v_ashrrev_i32_e32 v97, 31, v96
	v_lshlrev_b64 v[96:97], 12, v[96:97]
	v_lshl_add_u64 v[98:99], v[192:193], 0, v[98:99]
	v_lshl_add_u64 v[96:97], v[192:193], 0, v[96:97]
	flat_load_dwordx4 v[108:111], v[98:99]
	flat_load_dwordx4 v[104:107], v[98:99] offset:64
	flat_load_dwordx4 v[100:103], v[96:97]
	s_nop 0
	flat_load_dwordx4 v[96:99], v[96:97] offset:64
	v_lshlrev_b32_e32 v130, 16, v156
	v_and_b32_e32 v131, 0xffff0000, v156
	v_lshlrev_b32_e32 v128, 16, v157
	v_and_b32_e32 v129, 0xffff0000, v157
	v_pk_fma_f32 v[128:129], v[94:95], v[126:127], v[128:129]
	v_pk_fma_f32 v[130:131], v[92:93], v[124:125], v[130:131]
	v_mul_f32_e32 v93, v129, v129
	v_mul_f32_e32 v92, v131, v131
	v_fmac_f32_e32 v92, v130, v130
	v_fmac_f32_e32 v93, v128, v128
	v_add_f32_e32 v156, v92, v93
	v_lshlrev_b32_e32 v92, 16, v158
	v_and_b32_e32 v93, 0xffff0000, v158
	v_lshlrev_b32_e32 v94, 16, v159
	v_and_b32_e32 v95, 0xffff0000, v159
	v_pk_fma_f32 v[158:159], v[90:91], v[122:123], v[94:95]
	v_pk_fma_f32 v[160:161], v[88:89], v[120:121], v[92:93]
	v_mul_f32_e32 v89, v159, v159
	v_mul_f32_e32 v88, v161, v161
	v_fmac_f32_e32 v88, v160, v160
	v_fmac_f32_e32 v89, v158, v158
	v_add_f32_e32 v88, v88, v89
	v_add_f32_e32 v92, v156, v88
	v_lshlrev_b32_e32 v88, 16, v148
	v_and_b32_e32 v89, 0xffff0000, v148
	v_lshlrev_b32_e32 v90, 16, v149
	v_and_b32_e32 v91, 0xffff0000, v149
	v_pk_fma_f32 v[148:149], v[86:87], v[118:119], v[90:91]
	v_pk_fma_f32 v[156:157], v[84:85], v[116:117], v[88:89]
	v_mul_f32_e32 v85, v149, v149
	v_mul_f32_e32 v84, v157, v157
	v_fmac_f32_e32 v84, v156, v156
	v_fmac_f32_e32 v85, v148, v148
	v_add_f32_e32 v84, v84, v85
	v_add_f32_e32 v88, v92, v84
	v_lshlrev_b32_e32 v84, 16, v150
	v_and_b32_e32 v85, 0xffff0000, v150
	v_lshlrev_b32_e32 v86, 16, v151
	v_and_b32_e32 v87, 0xffff0000, v151
	v_pk_fma_f32 v[150:151], v[82:83], v[114:115], v[86:87]
	v_pk_fma_f32 v[162:163], v[80:81], v[112:113], v[84:85]
	v_mul_f32_e32 v81, v151, v151
	v_mul_f32_e32 v80, v163, v163
	v_fmac_f32_e32 v80, v162, v162
	v_fmac_f32_e32 v81, v150, v150
	v_add_f32_e32 v80, v80, v81
	v_add_f32_e32 v80, v80, v88
	v_mov_b32_e32 v81, v80
	s_nop 1
	v_permlane16_swap_b32_e32 v80, v81
	v_add_f32_e32 v80, v80, v81
	v_mov_b32_e32 v81, v80
	s_nop 1
	v_permlane32_swap_b32_e32 v80, v81
	s_and_saveexec_b64 s[24:25], s[10:11]
	v_add_f32_e32 v80, v80, v81
	ds_write_b32 v222, v80 offset:512
	s_or_b64 exec, exec, s[24:25]
	v_lshlrev_b32_e32 v82, 16, v152
	v_and_b32_e32 v83, 0xffff0000, v152
	v_lshlrev_b32_e32 v80, 16, v153
	v_and_b32_e32 v81, 0xffff0000, v153
	v_pk_fma_f32 v[80:81], v[78:79], v[126:127], v[80:81]
	v_pk_fma_f32 v[84:85], v[76:77], v[124:125], v[82:83]
	v_mul_f32_e32 v77, v81, v81
	v_mul_f32_e32 v76, v85, v85
	v_fmac_f32_e32 v76, v84, v84
	v_fmac_f32_e32 v77, v80, v80
	v_add_f32_e32 v82, v76, v77
	v_lshlrev_b32_e32 v76, 16, v154
	v_and_b32_e32 v77, 0xffff0000, v154
	v_lshlrev_b32_e32 v78, 16, v155
	v_and_b32_e32 v79, 0xffff0000, v155
	v_pk_fma_f32 v[88:89], v[74:75], v[122:123], v[78:79]
	v_pk_fma_f32 v[92:93], v[72:73], v[120:121], v[76:77]
	v_mul_f32_e32 v73, v89, v89
	v_mul_f32_e32 v72, v93, v93
	v_fmac_f32_e32 v72, v92, v92
	v_fmac_f32_e32 v73, v88, v88
	v_add_f32_e32 v72, v72, v73
	v_add_f32_e32 v76, v82, v72
	v_lshlrev_b32_e32 v72, 16, v144
	v_and_b32_e32 v73, 0xffff0000, v144
	v_lshlrev_b32_e32 v74, 16, v145
	v_and_b32_e32 v75, 0xffff0000, v145
	v_pk_fma_f32 v[82:83], v[70:71], v[118:119], v[74:75]
	v_pk_fma_f32 v[86:87], v[68:69], v[116:117], v[72:73]
	v_mul_f32_e32 v69, v83, v83
	v_mul_f32_e32 v68, v87, v87
	v_fmac_f32_e32 v68, v86, v86
	v_fmac_f32_e32 v69, v82, v82
	v_add_f32_e32 v68, v68, v69
	v_add_f32_e32 v72, v76, v68
	v_lshlrev_b32_e32 v68, 16, v146
	v_and_b32_e32 v69, 0xffff0000, v146
	v_lshlrev_b32_e32 v70, 16, v147
	v_and_b32_e32 v71, 0xffff0000, v147
	v_pk_fma_f32 v[90:91], v[66:67], v[114:115], v[70:71]
	v_pk_fma_f32 v[94:95], v[64:65], v[112:113], v[68:69]
	v_mul_f32_e32 v65, v91, v91
	v_mul_f32_e32 v64, v95, v95
	v_fmac_f32_e32 v64, v94, v94
	v_fmac_f32_e32 v65, v90, v90
	v_add_f32_e32 v64, v64, v65
	v_add_f32_e32 v64, v64, v72
	v_mov_b32_e32 v65, v64
	s_nop 1
	v_permlane16_swap_b32_e32 v64, v65
	v_add_f32_e32 v64, v64, v65
	v_mov_b32_e32 v65, v64
	s_nop 1
	v_permlane32_swap_b32_e32 v64, v65
	s_and_saveexec_b64 s[24:25], s[10:11]
	v_add_f32_e32 v64, v64, v65
	ds_write_b32 v222, v64 offset:768
	s_or_b64 exec, exec, s[24:25]
	v_add_u32_e32 v64, s36, v212
	v_ashrrev_i32_e32 v65, 31, v64
	v_lshlrev_b64 v[66:67], 12, v[64:65]
	v_or_b32_e32 v64, 16, v64
	v_ashrrev_i32_e32 v65, 31, v64
	v_lshlrev_b64 v[64:65], 12, v[64:65]
	v_lshl_add_u64 v[66:67], v[192:193], 0, v[66:67]
	v_lshl_add_u64 v[64:65], v[192:193], 0, v[64:65]
	flat_load_dwordx4 v[76:79], v[66:67]
	flat_load_dwordx4 v[72:75], v[66:67] offset:64
	flat_load_dwordx4 v[68:71], v[64:65]
	s_nop 0
	flat_load_dwordx4 v[64:67], v[64:65] offset:64
	s_waitcnt vmcnt(0) lgkmcnt(0)
; #define PN_LOAD(k, xv) do { _Pragma("unroll") for (int mm = 0; mm < 2; ++mm) _Pragma("unroll") for (int bj = 0; bj < 2; ++bj) \
;             xv[mm][bj] = *(const u32x4*)(XH + (size_t)(u.pm * 256 + ((k) >> 1) * 128 + wr * 64 + (2 * ((k) & 1) + mm) * 16 + fr) * (2 * D) + col0 + bj * 32); } while (0)
;     __device__ __forceinline__ void epi(AccT& acc, const Unit& u, LAS unsigned char* lds, int wr, int wc, int fr, int fq) const {
;     ...
;         PN_LOAD(0, xa); PN_LOAD(1, xb); asm volatile("" ::: "memory"); PN_COMP(0, xa); PN_LOAD(2, xa); asm volatile("" ::: "memory"); PN_COMP(1, xb); PN_LOAD(3, xb); asm volatile("" ::: "memory"); PN_COMP(2, xa); PN_COMP(3, xb);
	v_lshlrev_b32_e32 v144, 16, v108
	v_and_b32_e32 v145, 0xffff0000, v108
	v_lshlrev_b32_e32 v108, 16, v109
	v_and_b32_e32 v109, 0xffff0000, v109
	v_pk_fma_f32 v[62:63], v[62:63], v[126:127], v[108:109]
	v_pk_fma_f32 v[60:61], v[60:61], v[124:125], v[144:145]
	v_mul_f32_e32 v109, v63, v63
	v_mul_f32_e32 v108, v61, v61
	v_fmac_f32_e32 v108, v60, v60
	v_fmac_f32_e32 v109, v62, v62
	v_add_f32_e32 v144, v108, v109
	v_lshlrev_b32_e32 v108, 16, v110
	v_and_b32_e32 v109, 0xffff0000, v110
	v_lshlrev_b32_e32 v110, 16, v111
	v_and_b32_e32 v111, 0xffff0000, v111
	v_pk_fma_f32 v[58:59], v[58:59], v[122:123], v[110:111]
	v_pk_fma_f32 v[56:57], v[56:57], v[120:121], v[108:109]
	v_mul_f32_e32 v109, v59, v59
	v_mul_f32_e32 v108, v57, v57
	v_fmac_f32_e32 v108, v56, v56
	v_fmac_f32_e32 v109, v58, v58
	v_add_f32_e32 v108, v108, v109
	v_add_f32_e32 v110, v144, v108
	v_lshlrev_b32_e32 v108, 16, v104
	v_and_b32_e32 v109, 0xffff0000, v104
	v_lshlrev_b32_e32 v104, 16, v105
	v_and_b32_e32 v105, 0xffff0000, v105
	v_pk_fma_f32 v[54:55], v[54:55], v[118:119], v[104:105]
	v_pk_fma_f32 v[52:53], v[52:53], v[116:117], v[108:109]
	v_mul_f32_e32 v105, v55, v55
	v_mul_f32_e32 v104, v53, v53
	v_fmac_f32_e32 v104, v52, v52
	v_fmac_f32_e32 v105, v54, v54
	v_add_f32_e32 v104, v104, v105
	v_add_f32_e32 v108, v110, v104
	v_lshlrev_b32_e32 v104, 16, v106
	v_and_b32_e32 v105, 0xffff0000, v106
	v_lshlrev_b32_e32 v106, 16, v107
	v_and_b32_e32 v107, 0xffff0000, v107
	v_pk_fma_f32 v[50:51], v[50:51], v[114:115], v[106:107]
	v_pk_fma_f32 v[48:49], v[48:49], v[112:113], v[104:105]
	v_mul_f32_e32 v105, v51, v51
	v_mul_f32_e32 v104, v49, v49
	v_fmac_f32_e32 v104, v48, v48
	v_fmac_f32_e32 v105, v50, v50
	v_add_f32_e32 v104, v104, v105
	v_add_f32_e32 v104, v104, v108
	v_mov_b32_e32 v105, v104
	s_nop 1
	v_permlane16_swap_b32_e32 v104, v105
	v_add_f32_e32 v104, v104, v105
	v_mov_b32_e32 v105, v104
	s_nop 1
	v_permlane32_swap_b32_e32 v104, v105
	s_and_saveexec_b64 s[24:25], s[10:11]
	v_add_f32_e32 v104, v104, v105
	ds_write_b32 v223, v104
	s_or_b64 exec, exec, s[24:25]
	v_lshlrev_b32_e32 v104, 16, v100
	v_and_b32_e32 v105, 0xffff0000, v100
	v_lshlrev_b32_e32 v100, 16, v101
	v_and_b32_e32 v101, 0xffff0000, v101
	v_pk_fma_f32 v[46:47], v[46:47], v[126:127], v[100:101]
	v_pk_fma_f32 v[44:45], v[44:45], v[124:125], v[104:105]
	v_mul_f32_e32 v101, v47, v47
	v_mul_f32_e32 v100, v45, v45
	v_fmac_f32_e32 v100, v44, v44
	v_fmac_f32_e32 v101, v46, v46
	v_add_f32_e32 v104, v100, v101
	v_lshlrev_b32_e32 v100, 16, v102
	v_and_b32_e32 v101, 0xffff0000, v102
	v_lshlrev_b32_e32 v102, 16, v103
	v_and_b32_e32 v103, 0xffff0000, v103
	v_pk_fma_f32 v[42:43], v[42:43], v[122:123], v[102:103]
	v_pk_fma_f32 v[40:41], v[40:41], v[120:121], v[100:101]
	v_mul_f32_e32 v101, v43, v43
	v_mul_f32_e32 v100, v41, v41
	v_fmac_f32_e32 v100, v40, v40
	v_fmac_f32_e32 v101, v42, v42
	v_add_f32_e32 v100, v100, v101
	v_add_f32_e32 v102, v104, v100
	v_lshlrev_b32_e32 v100, 16, v96
	v_and_b32_e32 v101, 0xffff0000, v96
	v_lshlrev_b32_e32 v96, 16, v97
	v_and_b32_e32 v97, 0xffff0000, v97
	v_pk_fma_f32 v[38:39], v[38:39], v[118:119], v[96:97]
	v_pk_fma_f32 v[36:37], v[36:37], v[116:117], v[100:101]
	v_mul_f32_e32 v97, v39, v39
	v_mul_f32_e32 v96, v37, v37
	v_fmac_f32_e32 v96, v36, v36
	v_fmac_f32_e32 v97, v38, v38
	v_add_f32_e32 v96, v96, v97
	v_add_f32_e32 v100, v102, v96
	v_lshlrev_b32_e32 v96, 16, v98
	v_and_b32_e32 v97, 0xffff0000, v98
	v_lshlrev_b32_e32 v98, 16, v99
	v_and_b32_e32 v99, 0xffff0000, v99
	v_pk_fma_f32 v[34:35], v[34:35], v[114:115], v[98:99]
	v_pk_fma_f32 v[32:33], v[32:33], v[112:113], v[96:97]
	v_mul_f32_e32 v97, v35, v35
	v_mul_f32_e32 v96, v33, v33
	v_fmac_f32_e32 v96, v32, v32
	v_fmac_f32_e32 v97, v34, v34
	v_add_f32_e32 v96, v96, v97
	v_add_f32_e32 v96, v96, v100
	v_mov_b32_e32 v97, v96
	s_nop 1
	v_permlane16_swap_b32_e32 v96, v97
	v_add_f32_e32 v96, v96, v97
	v_mov_b32_e32 v97, v96
	s_nop 1
	v_permlane32_swap_b32_e32 v96, v97
	s_and_saveexec_b64 s[24:25], s[10:11]
	v_add_f32_e32 v96, v96, v97
	ds_write_b32 v223, v96 offset:256
	s_or_b64 exec, exec, s[24:25]
	v_lshlrev_b32_e32 v96, 16, v76
	v_and_b32_e32 v97, 0xffff0000, v76
	v_lshlrev_b32_e32 v76, 16, v77
	v_and_b32_e32 v77, 0xffff0000, v77
	v_pk_fma_f32 v[30:31], v[30:31], v[126:127], v[76:77]
	v_pk_fma_f32 v[28:29], v[28:29], v[124:125], v[96:97]
	v_mul_f32_e32 v77, v31, v31
	v_mul_f32_e32 v76, v29, v29
	v_fmac_f32_e32 v76, v28, v28
	v_fmac_f32_e32 v77, v30, v30
	v_add_f32_e32 v96, v76, v77
	v_lshlrev_b32_e32 v76, 16, v78
	v_and_b32_e32 v77, 0xffff0000, v78
; #define LAS __attribute__((address_space(3)))
; #define ESTAMP(i) do { if (PROBE_K >= 100 && MODE == 1 && blockIdx.x == 0 && wr * 4 + wc == 0 && fr + 16 * fq == 0 && tmo != nullptr) { ((unsigned long long*)tmo)[25600 + 64 + (i)] = __builtin_amdgcn_s_memrealtime(); } } while (0)
; #define PN_LOAD(k, xv) do { _Pragma("unroll") for (int mm = 0; mm < 2; ++mm) _Pragma("unroll") for (int bj = 0; bj < 2; ++bj) \
;             xv[mm][bj] = *(const u32x4*)(XH + (size_t)(u.pm * 256 + ((k) >> 1) * 128 + wr * 64 + (2 * ((k) & 1) + mm) * 16 + fr) * (2 * D) + col0 + bj * 32); } while (0)
;     __device__ __forceinline__ void epi(AccT& acc, const Unit& u, LAS unsigned char* lds, int wr, int wc, int fr, int fq) const {
;     ...
;         PN_LOAD(0, xa); PN_LOAD(1, xb); asm volatile("" ::: "memory"); PN_COMP(0, xa); PN_LOAD(2, xa); asm volatile("" ::: "memory"); PN_COMP(1, xb); PN_LOAD(3, xb); asm volatile("" ::: "memory"); PN_COMP(2, xa); PN_COMP(3, xb);
;     ...
;         asm volatile("s_waitcnt lgkmcnt(0)" ::: "memory"); __builtin_amdgcn_s_barrier(); asm volatile("" ::: "memory");
;         ESTAMP(1);
;         const int row = wid * 32 + (lane & 31);
;         if (lane < 32) { const f32x4 p4 = *(const LAS f32x4*)(Pl + row * 4); const float tot = (p4[0] + p4[1]) + (p4[2] + p4[3]);
;             __hip_atomic_store(xbuf + (size_t)(u.pm * 256 + row) * 4 + u.pn, __builtin_bit_cast(unsigned, tot), __ATOMIC_RELAXED, __HIP_MEMORY_SCOPE_AGENT); }
;     ...
;             if (tid < 256) { const int c = u.pn * 256 + tid; svl[tid] = wf[c] * (1.f + shp[(size_t)b * 6 * D + D + c]); tvl[tid] = shp[(size_t)b * 6 * D + c]; }
	v_lshlrev_b32_e32 v78, 16, v79
	v_and_b32_e32 v79, 0xffff0000, v79
	v_pk_fma_f32 v[26:27], v[26:27], v[122:123], v[78:79]
	v_pk_fma_f32 v[24:25], v[24:25], v[120:121], v[76:77]
	v_mul_f32_e32 v77, v27, v27
	v_mul_f32_e32 v76, v25, v25
	v_fmac_f32_e32 v76, v24, v24
	v_fmac_f32_e32 v77, v26, v26
	v_add_f32_e32 v76, v76, v77
	v_add_f32_e32 v78, v96, v76
	v_lshlrev_b32_e32 v76, 16, v72
	v_and_b32_e32 v77, 0xffff0000, v72
	v_lshlrev_b32_e32 v72, 16, v73
	v_and_b32_e32 v73, 0xffff0000, v73
	v_pk_fma_f32 v[22:23], v[22:23], v[118:119], v[72:73]
	v_pk_fma_f32 v[20:21], v[20:21], v[116:117], v[76:77]
	v_mul_f32_e32 v73, v23, v23
	v_mul_f32_e32 v72, v21, v21
	v_fmac_f32_e32 v72, v20, v20
	v_fmac_f32_e32 v73, v22, v22
	v_add_f32_e32 v72, v72, v73
	v_add_f32_e32 v76, v78, v72
	v_lshlrev_b32_e32 v72, 16, v74
	v_and_b32_e32 v73, 0xffff0000, v74
	v_lshlrev_b32_e32 v74, 16, v75
	v_and_b32_e32 v75, 0xffff0000, v75
	v_pk_fma_f32 v[18:19], v[18:19], v[114:115], v[74:75]
	v_pk_fma_f32 v[16:17], v[16:17], v[112:113], v[72:73]
	v_mul_f32_e32 v73, v19, v19
	v_mul_f32_e32 v72, v17, v17
	v_fmac_f32_e32 v72, v16, v16
	v_fmac_f32_e32 v73, v18, v18
	v_add_f32_e32 v72, v72, v73
	v_add_f32_e32 v72, v72, v76
	v_mov_b32_e32 v73, v72
	s_nop 1
	v_permlane16_swap_b32_e32 v72, v73
	v_add_f32_e32 v72, v72, v73
	v_mov_b32_e32 v73, v72
	s_nop 1
	v_permlane32_swap_b32_e32 v72, v73
	s_and_saveexec_b64 s[24:25], s[10:11]
	v_add_f32_e32 v72, v72, v73
	ds_write_b32 v223, v72 offset:512
	s_or_b64 exec, exec, s[24:25]
	v_lshlrev_b32_e32 v72, 16, v68
	v_and_b32_e32 v73, 0xffff0000, v68
	v_lshlrev_b32_e32 v68, 16, v69
	v_and_b32_e32 v69, 0xffff0000, v69
	v_pk_fma_f32 v[14:15], v[14:15], v[126:127], v[68:69]
	v_pk_fma_f32 v[12:13], v[12:13], v[124:125], v[72:73]
	v_mul_f32_e32 v69, v15, v15
	v_mul_f32_e32 v68, v13, v13
	v_fmac_f32_e32 v68, v12, v12
	v_fmac_f32_e32 v69, v14, v14
	v_add_f32_e32 v72, v68, v69
	v_lshlrev_b32_e32 v68, 16, v70
	v_and_b32_e32 v69, 0xffff0000, v70
	v_lshlrev_b32_e32 v70, 16, v71
	v_and_b32_e32 v71, 0xffff0000, v71
	v_pk_fma_f32 v[10:11], v[10:11], v[122:123], v[70:71]
	v_pk_fma_f32 v[8:9], v[8:9], v[120:121], v[68:69]
	v_mul_f32_e32 v69, v11, v11
	v_mul_f32_e32 v68, v9, v9
	v_fmac_f32_e32 v68, v8, v8
	v_fmac_f32_e32 v69, v10, v10
	v_add_f32_e32 v68, v68, v69
	v_add_f32_e32 v70, v72, v68
	v_lshlrev_b32_e32 v68, 16, v64
	v_and_b32_e32 v69, 0xffff0000, v64
	v_lshlrev_b32_e32 v64, 16, v65
	v_and_b32_e32 v65, 0xffff0000, v65
	v_pk_fma_f32 v[6:7], v[6:7], v[118:119], v[64:65]
	v_pk_fma_f32 v[4:5], v[4:5], v[116:117], v[68:69]
	v_mul_f32_e32 v65, v7, v7
	v_mul_f32_e32 v64, v5, v5
	v_fmac_f32_e32 v64, v4, v4
	v_fmac_f32_e32 v65, v6, v6
	v_add_f32_e32 v64, v64, v65
	v_add_f32_e32 v68, v70, v64
	v_lshlrev_b32_e32 v64, 16, v66
	v_and_b32_e32 v65, 0xffff0000, v66
	v_lshlrev_b32_e32 v66, 16, v67
	v_and_b32_e32 v67, 0xffff0000, v67
	v_pk_fma_f32 v[2:3], v[2:3], v[114:115], v[66:67]
	v_pk_fma_f32 v[0:1], v[0:1], v[112:113], v[64:65]
	v_mul_f32_e32 v65, v3, v3
	v_mul_f32_e32 v64, v1, v1
	v_fmac_f32_e32 v64, v0, v0
	v_fmac_f32_e32 v65, v2, v2
	v_add_f32_e32 v64, v64, v65
	v_add_f32_e32 v64, v64, v68
	v_mov_b32_e32 v65, v64
	s_nop 1
	v_permlane16_swap_b32_e32 v64, v65
	v_add_f32_e32 v64, v64, v65
	v_mov_b32_e32 v65, v64
	s_nop 1
	v_permlane32_swap_b32_e32 v64, v65
	s_and_saveexec_b64 s[24:25], s[10:11]
	v_add_f32_e32 v64, v64, v65
	ds_write_b32 v223, v64 offset:768
	s_or_b64 exec, exec, s[24:25]
	s_waitcnt lgkmcnt(0)
	s_barrier
	s_and_saveexec_b64 s[24:25], s[18:19]
	v_add_u32_e32 v64, s63, v201
	v_readlane_b32 s44, v252, 54
	v_ashrrev_i32_e32 v65, 31, v64
	s_add_u32 s26, s44, s26
	v_lshlrev_b64 v[64:65], 2, v[64:65]
	s_addc_u32 s27, s3, s27
	v_lshl_add_u64 v[68:69], s[42:43], 0, v[64:65]
	v_lshl_add_u64 v[64:65], s[26:27], 0, v[64:65]
	global_load_dword v228, v[68:69], off
	v_add_co_u32_e32 v68, vcc, 0x1000, v64
	global_load_dword v229, v[64:65], off
	s_nop 0
	v_addc_co_u32_e32 v69, vcc, 0, v65, vcc
	global_load_dword v230, v[68:69], off
	s_mov_b64 exec, s[24:25]
	v_add_u32_e32 v64, s75, v203
	v_ashrrev_i32_e32 v65, 31, v64
	s_and_saveexec_b64 s[24:25], s[12:13]
	s_cbranch_execz .LBB0_1019
	ds_read_b128 v[66:69], v218
	s_ashr_i32 s75, s74, 31
	s_waitcnt lgkmcnt(0)
	v_mov_b32_e32 v70, v67
	v_mov_b32_e32 v71, v68
	v_mov_b32_e32 v67, v69
	v_pk_add_f32 v[66:67], v[70:71], v[66:67]
	v_lshl_add_u64 v[68:69], v[64:65], 4, s[30:31]
	v_pk_add_f32 v[66:67], v[66:67], v[66:67] op_sel:[0,1] op_sel_hi:[1,0]
	v_lshl_add_u64 v[68:69], s[74:75], 2, v[68:69]
	global_store_dword v[68:69], v66, off sc1

;     __device__ __forceinline__ void epi(AccT& acc, const Unit& u, LAS unsigned char* lds, int wr, int wc, int fr, int fq) const {
;     ...
;             if (tid < 256) { const int c = u.pn * 256 + tid; svl[tid] = wf[c] * (1.f + shp[(size_t)b * 6 * D + D + c]); tvl[tid] = shp[(size_t)b * 6 * D + c]; }
;             asm volatile("s_waitcnt vmcnt(0) lgkmcnt(0)" ::: "memory"); __builtin_amdgcn_s_barrier(); asm volatile("" ::: "memory");
.LBB0_1041:
	s_or_b64 exec, exec, s[74:75]
	s_waitcnt lgkmcnt(0)
	s_barrier
	s_and_saveexec_b64 s[24:25], s[18:19]
	s_cbranch_execz .LBB0_1043
	s_waitcnt vmcnt(0)
	ds_write_b32 v206, v229
	v_add_f32_e32 v230, 1.0, v230
	v_mul_f32_e32 v228, v228, v230
	ds_write_b32 v205, v228
